# loop-edge VALU trimming: last exp folded into psb in-gap, duplicate v_mov alpha=1.0 removed (2 fewer VALU per iteration)
# baseline (speedup 1.0000x reference)
; #define SBAR() __builtin_amdgcn_sched_barrier(0)
; __device__ __forceinline__ unsigned cvtpk(float lo, float hi) { unsigned r; asm volatile("v_cvt_pk_bf16_f32 %0, %1, %2" : "=v"(r) : "v"(lo), "v"(hi)); return r; }
; __device__ __forceinline__ void qkt_fin(f32x16& n0, f32x16& n1, const bf16_t* Ks, const bf16x8* qr, const f32x16& negm, int r32, int hi, ...
;   float psa = 0.f, psb = 0.f; u32x4 wa, wb, wc, wd;
;     ...
; #pragma unroll
;   for (int d0 = 0; d0 < 8; ++d0) { int cb = (d0 * 16 + hi * 8) * 2;
;     bf16x8 b0 = *reinterpret_cast<const bf16x8*>((const char*)Ks + KSWZ(r32, cb));
;     bf16x8 b1 = *reinterpret_cast<const bf16x8*>((const char*)Ks + KSWZ(32 + r32, cb));
;     SBAR(); if (d0 == 0) n0 = __builtin_amdgcn_mfma_f32_32x32x16_bf16(b0, qr[0], negm, 0, 0, 0); else n0 = __builtin_amdgcn_mfma_f32_32x32x16_bf16(b0, qr[d0], n0, 0, 0, 0);
;     SBAR(); QF_CHUNK(2 * d0); SBAR();
;     if (d0 == 0) n1 = __builtin_amdgcn_mfma_f32_32x32x16_bf16(b1, qr[0], negm, 0, 0, 0); else n1 = __builtin_amdgcn_mfma_f32_32x32x16_bf16(b1, qr[d0], n1, 0, 0, 0);
;     SBAR(); QF_CHUNK(2 * d0 + 1); SBAR();
;     if (d0 == 7) { vf8_read<0>(vf0, vbv); SBAR(); } }
;     ...
;   psb += P1[15]; wd[3] = cvtpk(P1[14], P1[15]);
;   l_reg = l_reg * alpha + (psa + psb);
;   pa0 = *reinterpret_cast<bf16x8*>(&wa); pa1 = *reinterpret_cast<bf16x8*>(&wb); pa2 = *reinterpret_cast<bf16x8*>(&wc); pa3 = *reinterpret_cast<bf16x8*>(&wd);
; }
.LBB0_453:
	s_add_i32 s97, s96, 0xffff8000
	s_xor_b32 s98, s96, 0x10000
	s_add_i32 s99, s96, 0x8000
	s_and_b32 s99, s99, 0x18000
	ds_read_b128 v[98:101], v184 offset:49152
	ds_read_b128 v[196:199], v184 offset:57344
	v_xor_b32_e32 v184, 0x10000, v184
	ds_read_b128 v[248:251], v185 offset:49152
	ds_read_b128 v[252:255], v185 offset:57344
	v_xor_b32_e32 v185, 0x10000, v185
	v_add_u32_e32 v0, s97, v235
	s_waitcnt lgkmcnt(3)
	v_mfma_f32_32x32x16_bf16 v[132:147], v[98:101], v[152:155], v[66:81]
	v_exp_f32_e32 v82, v82
	s_waitcnt lgkmcnt(2)
	v_mfma_f32_32x32x16_bf16 v[98:113], v[196:199], v[152:155], v[66:81]
	v_exp_f32_e32 v83, v83
	v_add_f32_e32 v245, v115, v114
	v_cvt_pk_bf16_f32 v196, v114, v115
	ds_read_b128 v[202:205], v186 offset:49152
	ds_read_b128 v[206:209], v186 offset:57344
	v_xor_b32_e32 v186, 0x10000, v186
	s_waitcnt lgkmcnt(3)
	v_mfma_f32_32x32x16_bf16 v[132:147], v[248:251], v[160:163], v[132:147]
	v_exp_f32_e32 v84, v84
	v_add_f32_e32 v245, v116, v245
	v_add_f32_e32 v246, v82, v83
	s_waitcnt lgkmcnt(2)
	v_mfma_f32_32x32x16_bf16 v[98:113], v[252:255], v[160:163], v[98:113]
	v_exp_f32_e32 v85, v85
	v_add_f32_e32 v245, v117, v245
	v_add_f32_e32 v246, v246, v84
	v_cvt_pk_bf16_f32 v197, v116, v117
	v_cvt_pk_bf16_f32 v200, v82, v83
	ds_read_b128 v[248:251], v187 offset:49152
	ds_read_b128 v[252:255], v187 offset:57344
	v_xor_b32_e32 v187, 0x10000, v187
	s_waitcnt lgkmcnt(3)
	v_mfma_f32_32x32x16_bf16 v[132:147], v[202:205], v[148:151], v[132:147]
	v_exp_f32_e32 v86, v86
	v_add_f32_e32 v245, v118, v245
	v_add_f32_e32 v246, v246, v85
	s_waitcnt lgkmcnt(2)
	v_mfma_f32_32x32x16_bf16 v[98:113], v[206:209], v[148:151], v[98:113]
	v_exp_f32_e32 v87, v87
	v_add_f32_e32 v245, v119, v245
	v_add_f32_e32 v246, v246, v86
	v_cvt_pk_bf16_f32 v198, v118, v119
	v_cvt_pk_bf16_f32 v201, v84, v85
	ds_read_b128 v[204:207], v188 offset:49152
	ds_read_b128 v[208:211], v188 offset:57344
	v_xor_b32_e32 v188, 0x10000, v188
	s_waitcnt lgkmcnt(3)
	v_mfma_f32_32x32x16_bf16 v[132:147], v[248:251], v[156:159], v[132:147]
	v_exp_f32_e32 v88, v88
	v_add_f32_e32 v245, v120, v245
	v_add_f32_e32 v246, v246, v87
	s_waitcnt lgkmcnt(2)
	v_mfma_f32_32x32x16_bf16 v[98:113], v[252:255], v[156:159], v[98:113]
	v_exp_f32_e32 v89, v89
	v_add_f32_e32 v245, v121, v245
	v_add_f32_e32 v246, v246, v88
	v_cvt_pk_bf16_f32 v199, v120, v121
	v_cvt_pk_bf16_f32 v202, v86, v87
	ds_read_b128 v[248:251], v189 offset:49152
	ds_read_b128 v[252:255], v189 offset:57344
	v_xor_b32_e32 v189, 0x10000, v189
	s_waitcnt lgkmcnt(3)
	v_mfma_f32_32x32x16_bf16 v[132:147], v[204:207], v[168:171], v[132:147]
	v_exp_f32_e32 v90, v90
	v_add_f32_e32 v245, v122, v245
	v_add_f32_e32 v246, v246, v89
	s_waitcnt lgkmcnt(2)
	v_mfma_f32_32x32x16_bf16 v[98:113], v[208:211], v[168:171], v[98:113]
	v_exp_f32_e32 v91, v91
	v_add_f32_e32 v245, v123, v245
	v_add_f32_e32 v246, v246, v90
	v_cvt_pk_bf16_f32 v204, v122, v123
	v_cvt_pk_bf16_f32 v203, v88, v89
	ds_read_b128 v[114:117], v190 offset:49152
	ds_read_b128 v[118:121], v190 offset:57344
	v_xor_b32_e32 v190, 0x10000, v190
	s_waitcnt lgkmcnt(3)
	v_mfma_f32_32x32x16_bf16 v[132:147], v[248:251], v[176:179], v[132:147]
	v_exp_f32_e32 v92, v92
	v_add_f32_e32 v245, v124, v245
	v_add_f32_e32 v246, v246, v91
	s_waitcnt lgkmcnt(2)
	v_mfma_f32_32x32x16_bf16 v[98:113], v[252:255], v[176:179], v[98:113]
	v_exp_f32_e32 v93, v93
	v_add_f32_e32 v245, v125, v245
	v_add_f32_e32 v246, v246, v92
	v_cvt_pk_bf16_f32 v205, v124, v125
	v_cvt_pk_bf16_f32 v208, v90, v91
	ds_read_b128 v[248:251], v191 offset:49152
	ds_read_b128 v[252:255], v191 offset:57344
	v_xor_b32_e32 v191, 0x10000, v191
	s_waitcnt lgkmcnt(3)
	v_mfma_f32_32x32x16_bf16 v[132:147], v[114:117], v[164:167], v[132:147]
	v_exp_f32_e32 v94, v94
	v_add_f32_e32 v245, v126, v245
	v_add_f32_e32 v246, v246, v93
	s_waitcnt lgkmcnt(2)
	v_mfma_f32_32x32x16_bf16 v[98:113], v[118:121], v[164:167], v[98:113]
	v_exp_f32_e32 v95, v95
	v_add_f32_e32 v245, v127, v245
	v_add_f32_e32 v246, v246, v94
	v_cvt_pk_bf16_f32 v206, v126, v127
	v_cvt_pk_bf16_f32 v209, v92, v93
	s_waitcnt lgkmcnt(1)
	v_mfma_f32_32x32x16_bf16 v[132:147], v[248:251], v[172:175], v[132:147]
	v_exp_f32_e32 v96, v96
	v_add_f32_e32 v245, v128, v245
	v_add_f32_e32 v246, v246, v95
	s_waitcnt lgkmcnt(0)
	v_mfma_f32_32x32x16_bf16 v[98:113], v[252:255], v[172:175], v[98:113]
	v_exp_f32_e32 v97, v97
	v_add_f32_e32 v245, v129, v245
	v_add_f32_e32 v246, v246, v96
	v_cvt_pk_bf16_f32 v207, v128, v129
	v_cvt_pk_bf16_f32 v210, v94, v95
	v_add_f32_e32 v246, v246, v97
	v_cvt_pk_bf16_f32 v211, v96, v97
	ds_read_b64_tr_b16 v[94:95], v0 offset:0
	ds_read_b64_tr_b16 v[96:97], v0 offset:2048
	ds_read_b64_tr_b16 v[90:91], v0 offset:4096
	ds_read_b64_tr_b16 v[92:93], v0 offset:6144
	ds_read_b64_tr_b16 v[86:87], v0 offset:8192
	ds_read_b64_tr_b16 v[88:89], v0 offset:10240
	ds_read_b64_tr_b16 v[82:83], v0 offset:12288
	ds_read_b64_tr_b16 v[84:85], v0 offset:14336
	s_andn2_b64 s[8:9], exec, s[0:1]
	s_andn2_b64 vcc, exec, s[0:1]
	s_cbranch_vccnz .LBB0_456
; template <bool FIRST, bool DOEXP = true>
; __device__ __forceinline__ void partialSM(f32x16& p0, f32x16& p1, float& m_reg, f32x16& negm, float& alpha, const bool track = true) {
;     ...
;   float pmax = p0[0];
; #pragma unroll
;   for (int r = 1; r < 16; ++r) pmax = fmaxf(pmax, p0[r]);
; #pragma unroll
;   for (int r = 0; r < 16; ++r) pmax = fmaxf(pmax, p1[r]);
;   { auto rr = __builtin_amdgcn_permlane32_swap(__float_as_uint(pmax), __float_as_uint(pmax), false, false);
;     pmax = fmaxf(__uint_as_float(rr[0]), __uint_as_float(rr[1])); }
;   if (!FIRST && __builtin_expect(__all(pmax <= THRL), 1)) { alpha = 1.f; }
;   else { const float dl = FIRST ? pmax : fmaxf(pmax, 0.f); m_reg += dl; alpha = FIRST ? 1.f : __builtin_amdgcn_exp2f(-dl);
; #pragma unroll
;     for (int r = 0; r < 16; ++r) { p0[r] -= dl; p1[r] -= dl; }
; #pragma unroll
;     for (int r = 0; r < 16; ++r) negm[r] = -m_reg;
;     asm volatile("" : "+v"(negm)); }
	v_max_f32_e32 v114, v132, v133
	v_max3_f32 v114, v114, v134, v135
	v_max3_f32 v114, v114, v136, v137
	v_max3_f32 v114, v114, v138, v139
	v_max3_f32 v114, v114, v140, v141
	v_max3_f32 v114, v114, v142, v143
	v_max3_f32 v114, v114, v144, v145
	v_max3_f32 v114, v114, v146, v147
	v_max3_f32 v114, v114, v98, v99
	v_max3_f32 v114, v114, v100, v101
	v_max3_f32 v114, v114, v102, v103
	v_max3_f32 v114, v114, v104, v105
	v_max3_f32 v114, v114, v106, v107
	v_max3_f32 v114, v114, v108, v109
	v_max3_f32 v114, v114, v110, v111
	v_max3_f32 v114, v114, v112, v113
	v_mov_b32_e32 v115, v114
	s_nop 1
	v_permlane32_swap_b32_e32 v114, v115
	v_max_f32_e32 v114, v114, v115
	v_cmp_ge_f32_e32 vcc, s69, v114
	s_cmp_eq_u64 vcc, exec
	v_mov_b32_e32 v130, 1.0
	s_cbranch_scc1 .LBB0_457
	v_max_f32_e32 v66, v114, v114
	v_max_f32_e32 v66, 0, v66
	v_exp_f32_e64 v130, -v66
	v_add_f32_e32 v222, v222, v66
	v_sub_f32_e32 v147, v147, v66
	v_sub_f32_e32 v146, v146, v66
	v_sub_f32_e32 v145, v145, v66
	v_sub_f32_e32 v144, v144, v66
	v_sub_f32_e32 v143, v143, v66
	v_sub_f32_e32 v142, v142, v66
	v_sub_f32_e32 v141, v141, v66
	v_sub_f32_e32 v140, v140, v66
	v_sub_f32_e32 v139, v139, v66
	v_sub_f32_e32 v138, v138, v66
	v_sub_f32_e32 v137, v137, v66
	v_sub_f32_e32 v136, v136, v66
	v_sub_f32_e32 v135, v135, v66
	v_sub_f32_e32 v134, v134, v66
	v_sub_f32_e32 v133, v133, v66
	v_sub_f32_e32 v132, v132, v66
	v_sub_f32_e32 v113, v113, v66
	v_sub_f32_e32 v112, v112, v66
	v_sub_f32_e32 v111, v111, v66
	v_sub_f32_e32 v110, v110, v66
	v_sub_f32_e32 v109, v109, v66
	v_sub_f32_e32 v108, v108, v66
	v_sub_f32_e32 v107, v107, v66
	v_sub_f32_e32 v106, v106, v66
	v_sub_f32_e32 v105, v105, v66
	v_sub_f32_e32 v104, v104, v66
	v_sub_f32_e32 v103, v103, v66
	v_sub_f32_e32 v102, v102, v66
	v_sub_f32_e32 v101, v101, v66
	v_sub_f32_e32 v100, v100, v66
	v_sub_f32_e32 v99, v99, v66
	v_sub_f32_e32 v98, v98, v66
	v_xor_b32_e32 v66, 0x80000000, v222
	v_mov_b32_e32 v67, v66
	v_mov_b32_e32 v68, v66
	v_mov_b32_e32 v69, v66
	v_mov_b32_e32 v70, v66
	v_mov_b32_e32 v71, v66
	v_mov_b32_e32 v72, v66
	v_mov_b32_e32 v73, v66
	v_mov_b32_e32 v74, v66
	v_mov_b32_e32 v75, v66
	v_mov_b32_e32 v76, v66
	v_mov_b32_e32 v77, v66
	v_mov_b32_e32 v78, v66
	v_mov_b32_e32 v79, v66
	v_mov_b32_e32 v80, v66
	v_mov_b32_e32 v81, v66
	s_branch .LBB0_457

; #define SBAR() __builtin_amdgcn_sched_barrier(0)
; __device__ __forceinline__ unsigned cvtpk(float lo, float hi) { unsigned r; asm volatile("v_cvt_pk_bf16_f32 %0, %1, %2" : "=v"(r) : "v"(lo), "v"(hi)); return r; }
; template <bool FIRST, bool DOEXP = true>
; __device__ __forceinline__ void partialSM(f32x16& p0, f32x16& p1, float& m_reg, f32x16& negm, float& alpha, const bool track = true) {
;     ...
;   float pmax = p0[0];
; #pragma unroll
;   for (int r = 1; r < 16; ++r) pmax = fmaxf(pmax, p0[r]);
; #pragma unroll
;   for (int r = 0; r < 16; ++r) pmax = fmaxf(pmax, p1[r]);
;   { auto rr = __builtin_amdgcn_permlane32_swap(__float_as_uint(pmax), __float_as_uint(pmax), false, false);
;     pmax = fmaxf(__uint_as_float(rr[0]), __uint_as_float(rr[1])); }
;   if (!FIRST && __builtin_expect(__all(pmax <= THRL), 1)) { alpha = 1.f; }
; __device__ __forceinline__ void qkt_fin(f32x16& n0, f32x16& n1, const bf16_t* Ks, const bf16x8* qr, const f32x16& negm, int r32, int hi, ...
;   float psa = 0.f, psb = 0.f; u32x4 wa, wb, wc, wd;
;     ...
; #pragma unroll
;   for (int d0 = 0; d0 < 8; ++d0) { int cb = (d0 * 16 + hi * 8) * 2;
;     bf16x8 b0 = *reinterpret_cast<const bf16x8*>((const char*)Ks + KSWZ(r32, cb));
;     bf16x8 b1 = *reinterpret_cast<const bf16x8*>((const char*)Ks + KSWZ(32 + r32, cb));
;     SBAR(); if (d0 == 0) n0 = __builtin_amdgcn_mfma_f32_32x32x16_bf16(b0, qr[0], negm, 0, 0, 0); else n0 = __builtin_amdgcn_mfma_f32_32x32x16_bf16(b0, qr[d0], n0, 0, 0, 0);
;     SBAR(); QF_CHUNK(2 * d0); SBAR();
;     if (d0 == 0) n1 = __builtin_amdgcn_mfma_f32_32x32x16_bf16(b1, qr[0], negm, 0, 0, 0); else n1 = __builtin_amdgcn_mfma_f32_32x32x16_bf16(b1, qr[d0], n1, 0, 0, 0);
;     SBAR(); QF_CHUNK(2 * d0 + 1); SBAR();
;     if (d0 == 7) { vf8_read<0>(vf0, vbv); SBAR(); } }
;     ...
;   psb += P1[15]; wd[3] = cvtpk(P1[14], P1[15]);
;   l_reg = l_reg * alpha + (psa + psb);
;   pa0 = *reinterpret_cast<bf16x8*>(&wa); pa1 = *reinterpret_cast<bf16x8*>(&wb); pa2 = *reinterpret_cast<bf16x8*>(&wc); pa3 = *reinterpret_cast<bf16x8*>(&wd);
; }
.LBB0_461:
	s_waitcnt lgkmcnt(0)
	ds_read_b128 v[204:207], v184 offset:16384
	ds_read_b128 v[208:211], v184 offset:24576
	ds_read_b128 v[248:251], v185 offset:16384
	ds_read_b128 v[252:255], v185 offset:24576
	v_add_u32_e32 v203, s96, v235
	s_waitcnt lgkmcnt(3)
	v_mfma_f32_32x32x16_bf16 v[114:129], v[204:207], v[152:155], v[66:81]
	v_exp_f32_e32 v98, v98
	s_waitcnt lgkmcnt(2)
	v_mfma_f32_32x32x16_bf16 v[82:97], v[208:211], v[152:155], v[66:81]
	v_exp_f32_e32 v99, v99
	v_add_f32_e32 v201, v133, v132
	v_cvt_pk_bf16_f32 v132, v132, v133
	ds_read_b128 v[204:207], v186 offset:16384
	ds_read_b128 v[208:211], v186 offset:24576
	s_waitcnt lgkmcnt(3)
	v_mfma_f32_32x32x16_bf16 v[114:129], v[248:251], v[160:163], v[114:129]
	v_exp_f32_e32 v100, v100
	v_add_f32_e32 v201, v134, v201
	v_add_f32_e32 v202, v98, v99
	s_waitcnt lgkmcnt(2)
	v_mfma_f32_32x32x16_bf16 v[82:97], v[252:255], v[160:163], v[82:97]
	v_exp_f32_e32 v101, v101
	v_add_f32_e32 v201, v135, v201
	v_add_f32_e32 v202, v202, v100
	v_cvt_pk_bf16_f32 v133, v134, v135
	v_cvt_pk_bf16_f32 v196, v98, v99
	ds_read_b128 v[248:251], v187 offset:16384
	ds_read_b128 v[252:255], v187 offset:24576
	s_waitcnt lgkmcnt(3)
	v_mfma_f32_32x32x16_bf16 v[114:129], v[204:207], v[148:151], v[114:129]
	v_exp_f32_e32 v102, v102
	v_add_f32_e32 v201, v136, v201
	v_add_f32_e32 v202, v202, v101
	s_waitcnt lgkmcnt(2)
	v_mfma_f32_32x32x16_bf16 v[82:97], v[208:211], v[148:151], v[82:97]
	v_exp_f32_e32 v103, v103
	v_add_f32_e32 v201, v137, v201
	v_add_f32_e32 v202, v202, v102
	v_cvt_pk_bf16_f32 v134, v136, v137
	v_cvt_pk_bf16_f32 v197, v100, v101
	ds_read_b128 v[204:207], v188 offset:16384
	ds_read_b128 v[208:211], v188 offset:24576
	s_waitcnt lgkmcnt(3)
	v_mfma_f32_32x32x16_bf16 v[114:129], v[248:251], v[156:159], v[114:129]
	v_exp_f32_e32 v104, v104
	v_add_f32_e32 v201, v138, v201
	v_add_f32_e32 v202, v202, v103
	s_waitcnt lgkmcnt(2)
	v_mfma_f32_32x32x16_bf16 v[82:97], v[252:255], v[156:159], v[82:97]
	v_exp_f32_e32 v105, v105
	v_add_f32_e32 v201, v139, v201
	v_add_f32_e32 v202, v202, v104
	v_cvt_pk_bf16_f32 v135, v138, v139
	v_cvt_pk_bf16_f32 v198, v102, v103
	ds_read_b128 v[248:251], v189 offset:16384
	ds_read_b128 v[252:255], v189 offset:24576
	s_waitcnt lgkmcnt(3)
	v_mfma_f32_32x32x16_bf16 v[114:129], v[204:207], v[168:171], v[114:129]
	v_exp_f32_e32 v106, v106
	v_add_f32_e32 v201, v140, v201
	v_add_f32_e32 v202, v202, v105
	s_waitcnt lgkmcnt(2)
	v_mfma_f32_32x32x16_bf16 v[82:97], v[208:211], v[168:171], v[82:97]
	v_exp_f32_e32 v107, v107
	v_add_f32_e32 v201, v141, v201
	v_add_f32_e32 v202, v202, v106
	v_cvt_pk_bf16_f32 v136, v140, v141
	v_cvt_pk_bf16_f32 v199, v104, v105
	ds_read_b128 v[204:207], v190 offset:16384
	ds_read_b128 v[208:211], v190 offset:24576
	s_waitcnt lgkmcnt(3)
	v_mfma_f32_32x32x16_bf16 v[114:129], v[248:251], v[176:179], v[114:129]
	v_exp_f32_e32 v108, v108
	v_add_f32_e32 v201, v142, v201
	v_add_f32_e32 v202, v202, v107
	s_waitcnt lgkmcnt(2)
	v_mfma_f32_32x32x16_bf16 v[82:97], v[252:255], v[176:179], v[82:97]
	v_exp_f32_e32 v109, v109
	v_add_f32_e32 v201, v143, v201
	v_add_f32_e32 v202, v202, v108
	v_cvt_pk_bf16_f32 v137, v142, v143
	v_cvt_pk_bf16_f32 v140, v106, v107
	ds_read_b128 v[248:251], v191 offset:16384
	ds_read_b128 v[252:255], v191 offset:24576
	s_waitcnt lgkmcnt(3)
	v_mfma_f32_32x32x16_bf16 v[114:129], v[204:207], v[164:167], v[114:129]
	v_exp_f32_e32 v110, v110
	v_add_f32_e32 v201, v144, v201
	v_add_f32_e32 v202, v202, v109
	s_waitcnt lgkmcnt(2)
	v_mfma_f32_32x32x16_bf16 v[82:97], v[208:211], v[164:167], v[82:97]
	v_exp_f32_e32 v111, v111
	v_add_f32_e32 v201, v145, v201
	v_add_f32_e32 v202, v202, v110
	v_cvt_pk_bf16_f32 v138, v144, v145
	v_cvt_pk_bf16_f32 v141, v108, v109
	s_waitcnt lgkmcnt(1)
	v_mfma_f32_32x32x16_bf16 v[114:129], v[248:251], v[172:175], v[114:129]
	v_exp_f32_e32 v112, v112
	v_add_f32_e32 v201, v146, v201
	v_add_f32_e32 v202, v202, v111
	s_waitcnt lgkmcnt(0)
	v_mfma_f32_32x32x16_bf16 v[82:97], v[252:255], v[172:175], v[82:97]
	v_exp_f32_e32 v113, v113
	v_add_f32_e32 v201, v147, v201
	v_add_f32_e32 v202, v202, v112
	v_cvt_pk_bf16_f32 v139, v146, v147
	v_cvt_pk_bf16_f32 v142, v110, v111
	ds_read_b64_tr_b16 v[144:145], v203 offset:0
	ds_read_b64_tr_b16 v[146:147], v203 offset:2048
	s_nop 0
	ds_read_b64_tr_b16 v[106:107], v203 offset:4096
	ds_read_b64_tr_b16 v[108:109], v203 offset:6144
	ds_read_b64_tr_b16 v[102:103], v203 offset:8192
	ds_read_b64_tr_b16 v[104:105], v203 offset:10240
	ds_read_b64_tr_b16 v[98:99], v203 offset:12288
	ds_read_b64_tr_b16 v[100:101], v203 offset:14336
	v_cvt_pk_bf16_f32 v143, v112, v113
	s_and_b64 vcc, exec, s[8:9]
	v_mov_b32_e32 v200, 1.0
	s_cbranch_vccnz .LBB0_463
	v_max_f32_e32 v110, v114, v115
	v_max3_f32 v110, v110, v116, v117
	v_max3_f32 v110, v110, v118, v119
	v_max3_f32 v110, v110, v120, v121
	v_max3_f32 v110, v110, v122, v123
	v_max3_f32 v110, v110, v124, v125
	v_max3_f32 v110, v110, v126, v127
	v_max3_f32 v110, v110, v128, v129
	v_max3_f32 v110, v110, v82, v83
	v_max3_f32 v110, v110, v84, v85
	v_max3_f32 v110, v110, v86, v87
	v_max3_f32 v110, v110, v88, v89
	v_max3_f32 v110, v110, v90, v91
	v_max3_f32 v110, v110, v92, v93
	v_max3_f32 v110, v110, v94, v95
	v_max3_f32 v110, v110, v96, v97
	v_mov_b32_e32 v111, v110
	s_nop 1
	v_permlane32_swap_b32_e32 v110, v111
	v_max_f32_e32 v110, v110, v111
	v_cmp_ge_f32_e32 vcc, s69, v110
	s_cmp_eq_u64 vcc, exec
	s_cbranch_scc0 .LBB0_469

; #define SBAR() __builtin_amdgcn_sched_barrier(0)
; __device__ __forceinline__ unsigned cvtpk(float lo, float hi) { unsigned r; asm volatile("v_cvt_pk_bf16_f32 %0, %1, %2" : "=v"(r) : "v"(lo), "v"(hi)); return r; }
; #define SLOAD(k0) do { sr_.vs0 = *(const bf16x8*)(&Vh[(long)((k0) + sr) * LDK + sc]); sr_.vs1 = *(const bf16x8*)(&Vh[(long)((k0) + 32 + sr) * LDK + sc]); \
;     sr_.ks0 = *(const bf16x8*)(&Kh[(long)((k0) + sr) * LDK + sc]); sr_.ks1 = *(const bf16x8*)(&Kh[(long)((k0) + 32 + sr) * LDK + sc]); } while (0)
; #define SWRITE(so) do { *(bf16x8*)(lds + (so) + vst0) = sr_.vs0; *(bf16x8*)(lds + (so) + vst1) = sr_.vs1;          \
;     *(bf16x8*)(lds + (so) + kst0) = sr_.ks0; *(bf16x8*)(lds + (so) + kst1) = sr_.ks1; } while (0)
; #define SWAIT() asm volatile("s_waitcnt vmcnt(0)" ::: "memory")
; #define RESC(a) do { if (__any((a) < 1.f)) { if (hi == 0) al_l[r32] = (a); asm volatile("s_waitcnt lgkmcnt(0)" ::: "memory"); \
;     _Pragma("unroll") for (int d = 0; d < 4; ++d) _Pragma("unroll") for (int r = 0; r < 16; ++r) o[d][r] *= al_l[crow(r, hi)]; } } while (0)
; __device__ __forceinline__ void qkt_fin(f32x16& n0, f32x16& n1, const bf16_t* Ks, const bf16x8* qr, const f32x16& negm, int r32, int hi, ...
;     ...
;   psb += P1[15]; wd[3] = cvtpk(P1[14], P1[15]);
;   l_reg = l_reg * alpha + (psa + psb);
; __device__ __forceinline__ void attn_item(const bf16_t* __restrict__ Qb, const bf16_t* __restrict__ Kh, const bf16_t* __restrict__ Vh, const bf16_t* __restrict__ Zb, ...
;     ...
;   for (int j = 1; j + 1 < NT; j += 2) {
;     SBAR(); SLOAD((j + 1) * KVBLK); SBAR();
;     qkt_fin(pB0, pB1, (const bf16_t*)(lds + s_cur + KOFF), qr, negm, r32, hi, pA0, pA1, alA, l_reg, pa0, pa1, pa2, pa3, vfa, vb0 + s_prev); SBAR();
;     partialSM<false, false>(pB0, pB1, m_reg, negm, alB, track); SBAR(); pv_exp(o, vb0 + s_prev, pa0, pa1, pa2, pa3, pB0, vfa);
;     SWAIT(); SWRITE(s_next);
;     RESC(alB); __syncthreads(); ROT();
;     SBAR(); SLOAD((j + 2) * KVBLK); SBAR();
;     qkt_fin(pA0, pA1, (const bf16_t*)(lds + s_cur + KOFF), qr, negm, r32, hi, pB0, pB1, alB, l_reg, pa0, pa1, pa2, pa3, vfa, vb0 + s_prev); SBAR();
;     partialSM<false, false>(pA0, pA1, m_reg, negm, alA, track); SBAR(); pv_exp(o, vb0 + s_prev, pa0, pa1, pa2, pa3, pA0, vfa);
;     SWAIT(); SWRITE(s_next);
;     RESC(alA); __syncthreads(); ROT();
.LBB0_467:
	v_add_f32_e32 v98, v245, v246
	v_add_f32_e32 v99, v202, v113
	v_fmac_f32_e32 v98, v244, v219
	v_add_f32_e32 v219, v201, v99
	s_add_i32 s78, s78, 2
	v_fmac_f32_e32 v219, v98, v130
	s_cmpk_gt_u32 s78, 0xfc
	s_waitcnt lgkmcnt(0)
	s_cbranch_scc1 .LBB0_470
	s_xor_b32 s96, s96, 0x10000
	v_mov_b32_e32 v244, v200
	s_branch .LBB0_453

; #define SBAR() __builtin_amdgcn_sched_barrier(0)
; __device__ __forceinline__ unsigned cvtpk(float lo, float hi) { unsigned r; asm volatile("v_cvt_pk_bf16_f32 %0, %1, %2" : "=v"(r) : "v"(lo), "v"(hi)); return r; }
; __device__ __forceinline__ void qkt_fin(f32x16& n0, f32x16& n1, const bf16_t* Ks, const bf16x8* qr, const f32x16& negm, int r32, int hi, ...
;   float psa = 0.f, psb = 0.f; u32x4 wa, wb, wc, wd;
;     ...
; #pragma unroll
;   for (int d0 = 0; d0 < 8; ++d0) { int cb = (d0 * 16 + hi * 8) * 2;
;     bf16x8 b0 = *reinterpret_cast<const bf16x8*>((const char*)Ks + KSWZ(r32, cb));
;     bf16x8 b1 = *reinterpret_cast<const bf16x8*>((const char*)Ks + KSWZ(32 + r32, cb));
;     SBAR(); if (d0 == 0) n0 = __builtin_amdgcn_mfma_f32_32x32x16_bf16(b0, qr[0], negm, 0, 0, 0); else n0 = __builtin_amdgcn_mfma_f32_32x32x16_bf16(b0, qr[d0], n0, 0, 0, 0);
;     SBAR(); QF_CHUNK(2 * d0); SBAR();
;     if (d0 == 0) n1 = __builtin_amdgcn_mfma_f32_32x32x16_bf16(b1, qr[0], negm, 0, 0, 0); else n1 = __builtin_amdgcn_mfma_f32_32x32x16_bf16(b1, qr[d0], n1, 0, 0, 0);
;     SBAR(); QF_CHUNK(2 * d0 + 1); SBAR();
;     if (d0 == 7) { vf8_read<0>(vf0, vbv); SBAR(); } }
;     ...
;   psb += P1[15]; wd[3] = cvtpk(P1[14], P1[15]);
;   l_reg = l_reg * alpha + (psa + psb);
;   pa0 = *reinterpret_cast<bf16x8*>(&wa); pa1 = *reinterpret_cast<bf16x8*>(&wb); pa2 = *reinterpret_cast<bf16x8*>(&wc); pa3 = *reinterpret_cast<bf16x8*>(&wd);
; }
.Lh2_453:
	s_setprio 1
	s_add_i32 s97, s96, 0xffff8000
	s_xor_b32 s98, s96, 0x10000
	s_add_i32 s99, s96, 0x8000
	s_and_b32 s99, s99, 0x18000
	ds_read_b128 v[98:101], v184 offset:49152
	ds_read_b128 v[196:199], v184 offset:57344
	v_xor_b32_e32 v184, 0x10000, v184
	ds_read_b128 v[248:251], v185 offset:49152
	ds_read_b128 v[252:255], v185 offset:57344
	v_xor_b32_e32 v185, 0x10000, v185
	v_add_u32_e32 v0, s97, v235
	s_waitcnt lgkmcnt(3)
	v_mfma_f32_32x32x16_bf16 v[132:147], v[98:101], v[152:155], v[66:81]
	v_exp_f32_e32 v82, v82
	s_waitcnt lgkmcnt(2)
	v_mfma_f32_32x32x16_bf16 v[98:113], v[196:199], v[152:155], v[66:81]
	v_exp_f32_e32 v83, v83
	v_add_f32_e32 v245, v115, v114
	v_cvt_pk_bf16_f32 v196, v114, v115
	ds_read_b128 v[202:205], v186 offset:49152
	ds_read_b128 v[206:209], v186 offset:57344
	v_xor_b32_e32 v186, 0x10000, v186
	s_waitcnt lgkmcnt(3)
	v_mfma_f32_32x32x16_bf16 v[132:147], v[248:251], v[160:163], v[132:147]
	v_exp_f32_e32 v84, v84
	v_add_f32_e32 v245, v116, v245
	v_add_f32_e32 v246, v82, v83
	s_waitcnt lgkmcnt(2)
	v_mfma_f32_32x32x16_bf16 v[98:113], v[252:255], v[160:163], v[98:113]
	v_exp_f32_e32 v85, v85
	v_add_f32_e32 v245, v117, v245
	v_add_f32_e32 v246, v246, v84
	v_cvt_pk_bf16_f32 v197, v116, v117
	v_cvt_pk_bf16_f32 v200, v82, v83
	ds_read_b128 v[248:251], v187 offset:49152
	ds_read_b128 v[252:255], v187 offset:57344
	v_xor_b32_e32 v187, 0x10000, v187
	s_add_i32 s79, s99, s100
	s_add_i32 m0, s79, 0x4000
	s_add_i32 s79, s79, 0x6000
	global_load_lds_dwordx4 v180, s[82:83]
	s_waitcnt lgkmcnt(3)
	v_mfma_f32_32x32x16_bf16 v[132:147], v[202:205], v[148:151], v[132:147]
	v_exp_f32_e32 v86, v86
	v_add_f32_e32 v245, v118, v245
	v_add_f32_e32 v246, v246, v85
	s_waitcnt lgkmcnt(2)
	v_mfma_f32_32x32x16_bf16 v[98:113], v[206:209], v[148:151], v[98:113]
	v_exp_f32_e32 v87, v87
	v_add_f32_e32 v245, v119, v245
	v_add_f32_e32 v246, v246, v86
	v_cvt_pk_bf16_f32 v198, v118, v119
	v_cvt_pk_bf16_f32 v201, v84, v85
	ds_read_b128 v[204:207], v188 offset:49152
	ds_read_b128 v[208:211], v188 offset:57344
	v_xor_b32_e32 v188, 0x10000, v188
	s_mov_b32 m0, s79
	s_add_i32 s79, s99, s101
	global_load_lds_dwordx4 v182, s[82:83]
	s_waitcnt lgkmcnt(3)
	v_mfma_f32_32x32x16_bf16 v[132:147], v[248:251], v[156:159], v[132:147]
	v_exp_f32_e32 v88, v88
	v_add_f32_e32 v245, v120, v245
	v_add_f32_e32 v246, v246, v87
	s_waitcnt lgkmcnt(2)
	v_mfma_f32_32x32x16_bf16 v[98:113], v[252:255], v[156:159], v[98:113]
	v_exp_f32_e32 v89, v89
	v_add_f32_e32 v245, v121, v245
	v_add_f32_e32 v246, v246, v88
	v_cvt_pk_bf16_f32 v199, v120, v121
	v_cvt_pk_bf16_f32 v202, v86, v87
	ds_read_b128 v[248:251], v189 offset:49152
	ds_read_b128 v[252:255], v189 offset:57344
	v_xor_b32_e32 v189, 0x10000, v189
	s_mov_b32 m0, s79
	s_add_i32 s79, s79, 0x380
	global_load_lds_dwordx4 v214, s[82:83]
	s_waitcnt lgkmcnt(3)
	v_mfma_f32_32x32x16_bf16 v[132:147], v[204:207], v[168:171], v[132:147]
	v_exp_f32_e32 v90, v90
	v_add_f32_e32 v245, v122, v245
	v_add_f32_e32 v246, v246, v89
	s_waitcnt lgkmcnt(2)
	v_mfma_f32_32x32x16_bf16 v[98:113], v[208:211], v[168:171], v[98:113]
	v_exp_f32_e32 v91, v91
	v_add_f32_e32 v245, v123, v245
	v_add_f32_e32 v246, v246, v90
	v_cvt_pk_bf16_f32 v204, v122, v123
	v_cvt_pk_bf16_f32 v203, v88, v89
	ds_read_b128 v[114:117], v190 offset:49152
	ds_read_b128 v[118:121], v190 offset:57344
	v_xor_b32_e32 v190, 0x10000, v190
	s_mov_b32 m0, s79
	s_nop 0
	global_load_lds_dwordx4 v214, s[82:83] offset:128
	s_add_u32 s82, s82, s76
	s_addc_u32 s83, s83, s77
	s_waitcnt lgkmcnt(3)
	v_mfma_f32_32x32x16_bf16 v[132:147], v[248:251], v[176:179], v[132:147]
	v_exp_f32_e32 v92, v92
	v_add_f32_e32 v245, v124, v245
	v_add_f32_e32 v246, v246, v91
	s_waitcnt lgkmcnt(2)
	v_mfma_f32_32x32x16_bf16 v[98:113], v[252:255], v[176:179], v[98:113]
	v_exp_f32_e32 v93, v93
	v_add_f32_e32 v245, v125, v245
	v_add_f32_e32 v246, v246, v92
	v_cvt_pk_bf16_f32 v205, v124, v125
	v_cvt_pk_bf16_f32 v208, v90, v91
	ds_read_b128 v[248:251], v191 offset:49152
	ds_read_b128 v[252:255], v191 offset:57344
	v_xor_b32_e32 v191, 0x10000, v191
	s_waitcnt lgkmcnt(3)
	v_mfma_f32_32x32x16_bf16 v[132:147], v[114:117], v[164:167], v[132:147]
	v_exp_f32_e32 v94, v94
	v_add_f32_e32 v245, v126, v245
	v_add_f32_e32 v246, v246, v93
	s_waitcnt lgkmcnt(2)
	v_mfma_f32_32x32x16_bf16 v[98:113], v[118:121], v[164:167], v[98:113]
	v_exp_f32_e32 v95, v95
	v_add_f32_e32 v245, v127, v245
	v_add_f32_e32 v246, v246, v94
	v_cvt_pk_bf16_f32 v206, v126, v127
	v_cvt_pk_bf16_f32 v209, v92, v93
	s_waitcnt lgkmcnt(1)
	v_mfma_f32_32x32x16_bf16 v[132:147], v[248:251], v[172:175], v[132:147]
	v_exp_f32_e32 v96, v96
	v_add_f32_e32 v245, v128, v245
	v_add_f32_e32 v246, v246, v95
	s_waitcnt lgkmcnt(0)
	v_mfma_f32_32x32x16_bf16 v[98:113], v[252:255], v[172:175], v[98:113]
	v_exp_f32_e32 v97, v97
	v_add_f32_e32 v245, v129, v245
	v_add_f32_e32 v246, v246, v96
	v_cvt_pk_bf16_f32 v207, v128, v129
	v_cvt_pk_bf16_f32 v210, v94, v95
	v_add_f32_e32 v246, v246, v97
	v_cvt_pk_bf16_f32 v211, v96, v97
	ds_read_b64_tr_b16 v[94:95], v0 offset:0
	ds_read_b64_tr_b16 v[96:97], v0 offset:2048
	ds_read_b64_tr_b16 v[90:91], v0 offset:4096
	ds_read_b64_tr_b16 v[92:93], v0 offset:6144
	ds_read_b64_tr_b16 v[86:87], v0 offset:8192
	ds_read_b64_tr_b16 v[88:89], v0 offset:10240
	ds_read_b64_tr_b16 v[82:83], v0 offset:12288
	ds_read_b64_tr_b16 v[84:85], v0 offset:14336
	s_andn2_b64 s[8:9], exec, s[0:1]
	s_andn2_b64 vcc, exec, s[0:1]
	s_cbranch_vccnz .Lh2_456
; template <bool FIRST, bool DOEXP = true>
; __device__ __forceinline__ void partialSM(f32x16& p0, f32x16& p1, float& m_reg, f32x16& negm, float& alpha, const bool track = true) {
;     ...
;   float pmax = p0[0];
; #pragma unroll
;   for (int r = 1; r < 16; ++r) pmax = fmaxf(pmax, p0[r]);
; #pragma unroll
;   for (int r = 0; r < 16; ++r) pmax = fmaxf(pmax, p1[r]);
;   { auto rr = __builtin_amdgcn_permlane32_swap(__float_as_uint(pmax), __float_as_uint(pmax), false, false);
;     pmax = fmaxf(__uint_as_float(rr[0]), __uint_as_float(rr[1])); }
;   if (!FIRST && __builtin_expect(__all(pmax <= THRL), 1)) { alpha = 1.f; }
;   else { const float dl = FIRST ? pmax : fmaxf(pmax, 0.f); m_reg += dl; alpha = FIRST ? 1.f : __builtin_amdgcn_exp2f(-dl);
; #pragma unroll
;     for (int r = 0; r < 16; ++r) { p0[r] -= dl; p1[r] -= dl; }
; #pragma unroll
;     for (int r = 0; r < 16; ++r) negm[r] = -m_reg;
;     asm volatile("" : "+v"(negm)); }
	v_max_f32_e32 v114, v132, v133
	v_max3_f32 v114, v114, v134, v135
	v_max3_f32 v114, v114, v136, v137
	v_max3_f32 v114, v114, v138, v139
	v_max3_f32 v114, v114, v140, v141
	v_max3_f32 v114, v114, v142, v143
	v_max3_f32 v114, v114, v144, v145
	v_max3_f32 v114, v114, v146, v147
	v_max3_f32 v114, v114, v98, v99
	v_max3_f32 v114, v114, v100, v101
	v_max3_f32 v114, v114, v102, v103
	v_max3_f32 v114, v114, v104, v105
	v_max3_f32 v114, v114, v106, v107
	v_max3_f32 v114, v114, v108, v109
	v_max3_f32 v114, v114, v110, v111
	v_max3_f32 v114, v114, v112, v113
	v_mov_b32_e32 v115, v114
	s_nop 1
	v_permlane32_swap_b32_e32 v114, v115
	v_max_f32_e32 v114, v114, v115
	v_cmp_ge_f32_e32 vcc, s69, v114
	s_cmp_eq_u64 vcc, exec
	v_mov_b32_e32 v130, 1.0
	s_cbranch_scc1 .Lh2_457
	v_max_f32_e32 v66, v114, v114
	v_max_f32_e32 v66, 0, v66
	v_exp_f32_e64 v130, -v66
	v_add_f32_e32 v222, v222, v66
	v_sub_f32_e32 v147, v147, v66
	v_sub_f32_e32 v146, v146, v66
	v_sub_f32_e32 v145, v145, v66
	v_sub_f32_e32 v144, v144, v66
	v_sub_f32_e32 v143, v143, v66
	v_sub_f32_e32 v142, v142, v66
	v_sub_f32_e32 v141, v141, v66
	v_sub_f32_e32 v140, v140, v66
	v_sub_f32_e32 v139, v139, v66
	v_sub_f32_e32 v138, v138, v66
	v_sub_f32_e32 v137, v137, v66
	v_sub_f32_e32 v136, v136, v66
	v_sub_f32_e32 v135, v135, v66
	v_sub_f32_e32 v134, v134, v66
	v_sub_f32_e32 v133, v133, v66
	v_sub_f32_e32 v132, v132, v66
	v_sub_f32_e32 v113, v113, v66
	v_sub_f32_e32 v112, v112, v66
	v_sub_f32_e32 v111, v111, v66
	v_sub_f32_e32 v110, v110, v66
	v_sub_f32_e32 v109, v109, v66
	v_sub_f32_e32 v108, v108, v66
	v_sub_f32_e32 v107, v107, v66
	v_sub_f32_e32 v106, v106, v66
	v_sub_f32_e32 v105, v105, v66
	v_sub_f32_e32 v104, v104, v66
	v_sub_f32_e32 v103, v103, v66
	v_sub_f32_e32 v102, v102, v66
	v_sub_f32_e32 v101, v101, v66
	v_sub_f32_e32 v100, v100, v66
	v_sub_f32_e32 v99, v99, v66
	v_sub_f32_e32 v98, v98, v66
	v_xor_b32_e32 v66, 0x80000000, v222
	v_mov_b32_e32 v67, v66
	v_mov_b32_e32 v68, v66
	v_mov_b32_e32 v69, v66
	v_mov_b32_e32 v70, v66
	v_mov_b32_e32 v71, v66
	v_mov_b32_e32 v72, v66
	v_mov_b32_e32 v73, v66
	v_mov_b32_e32 v74, v66
	v_mov_b32_e32 v75, v66
	v_mov_b32_e32 v76, v66
	v_mov_b32_e32 v77, v66
	v_mov_b32_e32 v78, v66
	v_mov_b32_e32 v79, v66
	v_mov_b32_e32 v80, v66
	v_mov_b32_e32 v81, v66
	s_branch .Lh2_457

; #define SBAR() __builtin_amdgcn_sched_barrier(0)
; __device__ __forceinline__ unsigned cvtpk(float lo, float hi) { unsigned r; asm volatile("v_cvt_pk_bf16_f32 %0, %1, %2" : "=v"(r) : "v"(lo), "v"(hi)); return r; }
; __device__ __forceinline__ void qkt_fin(f32x16& n0, f32x16& n1, const bf16_t* Ks, const bf16x8* qr, const f32x16& negm, int r32, int hi, ...
;   float psa = 0.f, psb = 0.f; u32x4 wa, wb, wc, wd;
;     ...
; #pragma unroll
;   for (int d0 = 0; d0 < 8; ++d0) { int cb = (d0 * 16 + hi * 8) * 2;
;     bf16x8 b0 = *reinterpret_cast<const bf16x8*>((const char*)Ks + KSWZ(r32, cb));
;     bf16x8 b1 = *reinterpret_cast<const bf16x8*>((const char*)Ks + KSWZ(32 + r32, cb));
;     SBAR(); if (d0 == 0) n0 = __builtin_amdgcn_mfma_f32_32x32x16_bf16(b0, qr[0], negm, 0, 0, 0); else n0 = __builtin_amdgcn_mfma_f32_32x32x16_bf16(b0, qr[d0], n0, 0, 0, 0);
;     SBAR(); QF_CHUNK(2 * d0); SBAR();
;     if (d0 == 0) n1 = __builtin_amdgcn_mfma_f32_32x32x16_bf16(b1, qr[0], negm, 0, 0, 0); else n1 = __builtin_amdgcn_mfma_f32_32x32x16_bf16(b1, qr[d0], n1, 0, 0, 0);
;     SBAR(); QF_CHUNK(2 * d0 + 1); SBAR();
;     if (d0 == 7) { vf8_read<0>(vf0, vbv); SBAR(); } }
;     ...
;   psb += P1[15]; wd[3] = cvtpk(P1[14], P1[15]);
;   l_reg = l_reg * alpha + (psa + psb);
;   pa0 = *reinterpret_cast<bf16x8*>(&wa); pa1 = *reinterpret_cast<bf16x8*>(&wb); pa2 = *reinterpret_cast<bf16x8*>(&wc); pa3 = *reinterpret_cast<bf16x8*>(&wd);
; }
.Lh2_461:
	s_setprio 1
	s_waitcnt lgkmcnt(0)
	s_waitcnt vmcnt(0)
	s_barrier
	ds_read_b128 v[204:207], v184 offset:16384
	ds_read_b128 v[208:211], v184 offset:24576
	ds_read_b128 v[248:251], v185 offset:16384
	ds_read_b128 v[252:255], v185 offset:24576
	v_add_u32_e32 v203, s96, v235
	s_waitcnt lgkmcnt(3)
	v_mfma_f32_32x32x16_bf16 v[114:129], v[204:207], v[152:155], v[66:81]
	v_exp_f32_e32 v98, v98
	s_waitcnt lgkmcnt(2)
	v_mfma_f32_32x32x16_bf16 v[82:97], v[208:211], v[152:155], v[66:81]
	v_exp_f32_e32 v99, v99
	v_add_f32_e32 v201, v133, v132
	v_cvt_pk_bf16_f32 v132, v132, v133
	ds_read_b128 v[204:207], v186 offset:16384
	ds_read_b128 v[208:211], v186 offset:24576
	s_waitcnt lgkmcnt(3)
	v_mfma_f32_32x32x16_bf16 v[114:129], v[248:251], v[160:163], v[114:129]
	v_exp_f32_e32 v100, v100
	v_add_f32_e32 v201, v134, v201
	v_add_f32_e32 v202, v98, v99
	s_waitcnt lgkmcnt(2)
	v_mfma_f32_32x32x16_bf16 v[82:97], v[252:255], v[160:163], v[82:97]
	v_exp_f32_e32 v101, v101
	v_add_f32_e32 v201, v135, v201
	v_add_f32_e32 v202, v202, v100
	v_cvt_pk_bf16_f32 v133, v134, v135
	v_cvt_pk_bf16_f32 v196, v98, v99
	ds_read_b128 v[248:251], v187 offset:16384
	ds_read_b128 v[252:255], v187 offset:24576
	s_add_i32 s79, s98, s100
	s_add_i32 m0, s79, 0x4000
	s_add_i32 s79, s79, 0x6000
	global_load_lds_dwordx4 v180, s[82:83]
	s_waitcnt lgkmcnt(3)
	v_mfma_f32_32x32x16_bf16 v[114:129], v[204:207], v[148:151], v[114:129]
	v_exp_f32_e32 v102, v102
	v_add_f32_e32 v201, v136, v201
	v_add_f32_e32 v202, v202, v101
	s_waitcnt lgkmcnt(2)
	v_mfma_f32_32x32x16_bf16 v[82:97], v[208:211], v[148:151], v[82:97]
	v_exp_f32_e32 v103, v103
	v_add_f32_e32 v201, v137, v201
	v_add_f32_e32 v202, v202, v102
	v_cvt_pk_bf16_f32 v134, v136, v137
	v_cvt_pk_bf16_f32 v197, v100, v101
	ds_read_b128 v[204:207], v188 offset:16384
	ds_read_b128 v[208:211], v188 offset:24576
	s_mov_b32 m0, s79
	s_add_i32 s79, s98, s101
	global_load_lds_dwordx4 v182, s[82:83]
	s_waitcnt lgkmcnt(3)
	v_mfma_f32_32x32x16_bf16 v[114:129], v[248:251], v[156:159], v[114:129]
	v_exp_f32_e32 v104, v104
	v_add_f32_e32 v201, v138, v201
	v_add_f32_e32 v202, v202, v103
	s_waitcnt lgkmcnt(2)
	v_mfma_f32_32x32x16_bf16 v[82:97], v[252:255], v[156:159], v[82:97]
	v_exp_f32_e32 v105, v105
	v_add_f32_e32 v201, v139, v201
	v_add_f32_e32 v202, v202, v104
	v_cvt_pk_bf16_f32 v135, v138, v139
	v_cvt_pk_bf16_f32 v198, v102, v103
	ds_read_b128 v[248:251], v189 offset:16384
	ds_read_b128 v[252:255], v189 offset:24576
	s_mov_b32 m0, s79
	s_add_i32 s79, s79, 0x380
	global_load_lds_dwordx4 v214, s[82:83]
	s_waitcnt lgkmcnt(3)
	v_mfma_f32_32x32x16_bf16 v[114:129], v[204:207], v[168:171], v[114:129]
	v_exp_f32_e32 v106, v106
	v_add_f32_e32 v201, v140, v201
	v_add_f32_e32 v202, v202, v105
	s_waitcnt lgkmcnt(2)
	v_mfma_f32_32x32x16_bf16 v[82:97], v[208:211], v[168:171], v[82:97]
	v_exp_f32_e32 v107, v107
	v_add_f32_e32 v201, v141, v201
	v_add_f32_e32 v202, v202, v106
	v_cvt_pk_bf16_f32 v136, v140, v141
	v_cvt_pk_bf16_f32 v199, v104, v105
	ds_read_b128 v[204:207], v190 offset:16384
	ds_read_b128 v[208:211], v190 offset:24576
	s_mov_b32 m0, s79
	s_nop 0
	global_load_lds_dwordx4 v214, s[82:83] offset:128
	s_add_u32 s82, s82, s76
	s_addc_u32 s83, s83, s77
	s_waitcnt lgkmcnt(3)
	v_mfma_f32_32x32x16_bf16 v[114:129], v[248:251], v[176:179], v[114:129]
	v_exp_f32_e32 v108, v108
	v_add_f32_e32 v201, v142, v201
	v_add_f32_e32 v202, v202, v107
	s_waitcnt lgkmcnt(2)
	v_mfma_f32_32x32x16_bf16 v[82:97], v[252:255], v[176:179], v[82:97]
	v_exp_f32_e32 v109, v109
	v_add_f32_e32 v201, v143, v201
	v_add_f32_e32 v202, v202, v108
	v_cvt_pk_bf16_f32 v137, v142, v143
	v_cvt_pk_bf16_f32 v140, v106, v107
	ds_read_b128 v[248:251], v191 offset:16384
	ds_read_b128 v[252:255], v191 offset:24576
	s_waitcnt lgkmcnt(3)
	v_mfma_f32_32x32x16_bf16 v[114:129], v[204:207], v[164:167], v[114:129]
	v_exp_f32_e32 v110, v110
	v_add_f32_e32 v201, v144, v201
	v_add_f32_e32 v202, v202, v109
	s_waitcnt lgkmcnt(2)
	v_mfma_f32_32x32x16_bf16 v[82:97], v[208:211], v[164:167], v[82:97]
	v_exp_f32_e32 v111, v111
	v_add_f32_e32 v201, v145, v201
	v_add_f32_e32 v202, v202, v110
	v_cvt_pk_bf16_f32 v138, v144, v145
	v_cvt_pk_bf16_f32 v141, v108, v109
	s_waitcnt lgkmcnt(1)
	v_mfma_f32_32x32x16_bf16 v[114:129], v[248:251], v[172:175], v[114:129]
	v_exp_f32_e32 v112, v112
	v_add_f32_e32 v201, v146, v201
	v_add_f32_e32 v202, v202, v111
	s_waitcnt lgkmcnt(0)
	v_mfma_f32_32x32x16_bf16 v[82:97], v[252:255], v[172:175], v[82:97]
	v_exp_f32_e32 v113, v113
	v_add_f32_e32 v201, v147, v201
	v_add_f32_e32 v202, v202, v112
	v_cvt_pk_bf16_f32 v139, v146, v147
	v_cvt_pk_bf16_f32 v142, v110, v111
	ds_read_b64_tr_b16 v[144:145], v203 offset:0
	ds_read_b64_tr_b16 v[146:147], v203 offset:2048
	s_nop 0
	ds_read_b64_tr_b16 v[106:107], v203 offset:4096
	ds_read_b64_tr_b16 v[108:109], v203 offset:6144
	ds_read_b64_tr_b16 v[102:103], v203 offset:8192
	ds_read_b64_tr_b16 v[104:105], v203 offset:10240
	ds_read_b64_tr_b16 v[98:99], v203 offset:12288
	ds_read_b64_tr_b16 v[100:101], v203 offset:14336
	v_cvt_pk_bf16_f32 v143, v112, v113
	s_and_b64 vcc, exec, s[8:9]
	v_mov_b32_e32 v200, 1.0
	s_cbranch_vccnz .Lh2_463
	v_max_f32_e32 v110, v114, v115
	v_max3_f32 v110, v110, v116, v117
	v_max3_f32 v110, v110, v118, v119
	v_max3_f32 v110, v110, v120, v121
	v_max3_f32 v110, v110, v122, v123
	v_max3_f32 v110, v110, v124, v125
	v_max3_f32 v110, v110, v126, v127
	v_max3_f32 v110, v110, v128, v129
	v_max3_f32 v110, v110, v82, v83
	v_max3_f32 v110, v110, v84, v85
	v_max3_f32 v110, v110, v86, v87
	v_max3_f32 v110, v110, v88, v89
	v_max3_f32 v110, v110, v90, v91
	v_max3_f32 v110, v110, v92, v93
	v_max3_f32 v110, v110, v94, v95
	v_max3_f32 v110, v110, v96, v97
	v_mov_b32_e32 v111, v110
	s_nop 1
	v_permlane32_swap_b32_e32 v110, v111
	v_max_f32_e32 v110, v110, v111
	v_cmp_ge_f32_e32 vcc, s69, v110
	s_cmp_eq_u64 vcc, exec
	s_cbranch_scc0 .Lh2_469

; #define SBAR() __builtin_amdgcn_sched_barrier(0)
; __device__ __forceinline__ unsigned cvtpk(float lo, float hi) { unsigned r; asm volatile("v_cvt_pk_bf16_f32 %0, %1, %2" : "=v"(r) : "v"(lo), "v"(hi)); return r; }
; #define SLOAD(k0) do { sr_.vs0 = *(const bf16x8*)(&Vh[(long)((k0) + sr) * LDK + sc]); sr_.vs1 = *(const bf16x8*)(&Vh[(long)((k0) + 32 + sr) * LDK + sc]); \
;     sr_.ks0 = *(const bf16x8*)(&Kh[(long)((k0) + sr) * LDK + sc]); sr_.ks1 = *(const bf16x8*)(&Kh[(long)((k0) + 32 + sr) * LDK + sc]); } while (0)
; #define SWRITE(so) do { *(bf16x8*)(lds + (so) + vst0) = sr_.vs0; *(bf16x8*)(lds + (so) + vst1) = sr_.vs1;          \
;     *(bf16x8*)(lds + (so) + kst0) = sr_.ks0; *(bf16x8*)(lds + (so) + kst1) = sr_.ks1; } while (0)
; #define SWAIT() asm volatile("s_waitcnt vmcnt(0)" ::: "memory")
; #define RESC(a) do { if (__any((a) < 1.f)) { if (hi == 0) al_l[r32] = (a); asm volatile("s_waitcnt lgkmcnt(0)" ::: "memory"); \
;     _Pragma("unroll") for (int d = 0; d < 4; ++d) _Pragma("unroll") for (int r = 0; r < 16; ++r) o[d][r] *= al_l[crow(r, hi)]; } } while (0)
; __device__ __forceinline__ void qkt_fin(f32x16& n0, f32x16& n1, const bf16_t* Ks, const bf16x8* qr, const f32x16& negm, int r32, int hi, ...
;     ...
;   psb += P1[15]; wd[3] = cvtpk(P1[14], P1[15]);
;   l_reg = l_reg * alpha + (psa + psb);
; __device__ __forceinline__ void attn_item(const bf16_t* __restrict__ Qb, const bf16_t* __restrict__ Kh, const bf16_t* __restrict__ Vh, const bf16_t* __restrict__ Zb, ...
;     ...
;   for (int j = 1; j + 1 < NT; j += 2) {
;     SBAR(); SLOAD((j + 1) * KVBLK); SBAR();
;     qkt_fin(pB0, pB1, (const bf16_t*)(lds + s_cur + KOFF), qr, negm, r32, hi, pA0, pA1, alA, l_reg, pa0, pa1, pa2, pa3, vfa, vb0 + s_prev); SBAR();
;     partialSM<false, false>(pB0, pB1, m_reg, negm, alB, track); SBAR(); pv_exp(o, vb0 + s_prev, pa0, pa1, pa2, pa3, pB0, vfa);
;     SWAIT(); SWRITE(s_next);
;     RESC(alB); __syncthreads(); ROT();
;     SBAR(); SLOAD((j + 2) * KVBLK); SBAR();
;     qkt_fin(pA0, pA1, (const bf16_t*)(lds + s_cur + KOFF), qr, negm, r32, hi, pB0, pB1, alB, l_reg, pa0, pa1, pa2, pa3, vfa, vb0 + s_prev); SBAR();
;     partialSM<false, false>(pA0, pA1, m_reg, negm, alA, track); SBAR(); pv_exp(o, vb0 + s_prev, pa0, pa1, pa2, pa3, pA0, vfa);
;     SWAIT(); SWRITE(s_next);
;     RESC(alA); __syncthreads(); ROT();
.Lh2_467:
	v_add_f32_e32 v98, v245, v246
	v_add_f32_e32 v99, v202, v113
	v_fmac_f32_e32 v98, v244, v219
	v_add_f32_e32 v219, v201, v99
	s_add_i32 s78, s78, 2
	v_fmac_f32_e32 v219, v98, v130
	s_cmpk_gt_u32 s78, 0xfc
	s_waitcnt lgkmcnt(0)
	s_waitcnt vmcnt(0)
	s_barrier
	s_cbranch_scc1 .LBB0_470
	s_xor_b32 s96, s96, 0x10000
	v_mov_b32_e32 v244, v200
	s_branch .Lh2_453
